# v49 + residual GEMM: after a unit's epilogue stores, touch the next unit's residual tile (one dword per line) so its epilogue reads hit the memory-side cache
# baseline (speedup 1.0000x reference)
;     DI void operator()(const f32x4 (&acc)[2][2][4][2], const Unit& u, int wr, int wc, int fr, int fq) const {
;         const bool isc = u.pm >= (TL / BM);
;         const int bi = isc ? 16 : (u.pm >> 4);
;         const int rloc = (isc ? (u.pm - TL / BM) : u.pm) * BM + wr * 64 + fr;
;         const float* src = isc ? srcC : srcL; float* dst = isc ? dstC : dstL;
;         const int col0 = u.pn * BM + wc * 32 + 8 * fq;
;         const float* gp = gate + (size_t)bi * MODW + col0;
;         f32x4 gv[2][2];
; #pragma unroll
;         for (int bj = 0; bj < 2; ++bj)
; #pragma unroll
;             for (int n = 0; n < 2; ++n) gv[bj][n] = *(const f32x4*)(gp + bj * HALF + 4 * n) * coef;
; #pragma unroll
;         for (int ai = 0; ai < 2; ++ai)
; #pragma unroll
;             for (int mp = 0; mp < 2; ++mp) {
;                 f32x4 sv[2][2][2];
; #pragma unroll
;                 for (int m = 0; m < 2; ++m)
; #pragma unroll
;                     for (int bj = 0; bj < 2; ++bj)
; #pragma unroll
;                         for (int n = 0; n < 2; ++n) sv[m][bj][n] = *(const f32x4*)(src + (size_t)(rloc + ai * HALF + (2 * mp + m) * 16) * DM + col0 + bj * HALF + 4 * n);
; #pragma unroll
;                 for (int m = 0; m < 2; ++m)
; #pragma unroll
;                     for (int bj = 0; bj < 2; ++bj)
; #pragma unroll
;                         for (int n = 0; n < 2; ++n) *(f32x4*)(dst + (size_t)(rloc + ai * HALF + (2 * mp + m) * 16) * DM + col0 + bj * HALF + 4 * n) = sv[m][bj][n] + gv[bj][n] * acc[ai][bj][2 * mp + m][n];
;             }
.LBB0_498:
	s_lshl_b32 s22, s22, 8
	s_add_i32 s33, s22, 0xffff0000
	s_and_b64 s[30:31], exec, s[88:89]
	s_cselect_b32 s22, s33, s22
	v_lshl_or_b32 v184, s26, 8, v170
	s_lshl_b64 s[30:31], s[90:91], 2
	s_add_u32 s30, s68, s30
	s_addc_u32 s31, s69, s31
	v_lshlrev_b32_e32 v184, 2, v184
	v_add_u32_e32 v160, s22, v165
	s_nop 0
	global_load_dwordx4 v[140:143], v184, s[30:31]
	global_load_dwordx4 v[144:147], v184, s[30:31] offset:16
	global_load_dwordx4 v[148:151], v184, s[30:31] offset:512
	global_load_dwordx4 v[152:155], v184, s[30:31] offset:528
	v_lshl_add_u32 v160, v160, 12, v184
	v_add_u32_e32 v161, 0x10000, v160
	v_add_u32_e32 v166, 0x20000, v160
	v_add_u32_e32 v167, 0x30000, v160
	v_add_u32_e32 v156, 0x80000, v160
	v_add_u32_e32 v157, 0x90000, v160
	v_add_u32_e32 v158, 0xa0000, v160
	v_add_u32_e32 v159, 0xb0000, v160
	global_load_dwordx4 v[196:199], v160, s[86:87]
	global_load_dwordx4 v[200:203], v160, s[86:87] offset:16
	global_load_dwordx4 v[204:207], v160, s[86:87] offset:512
	global_load_dwordx4 v[208:211], v160, s[86:87] offset:528
	global_load_dwordx4 v[212:215], v161, s[86:87]
	global_load_dwordx4 v[216:219], v161, s[86:87] offset:16
	global_load_dwordx4 v[220:223], v161, s[86:87] offset:512
	global_load_dwordx4 v[224:227], v161, s[86:87] offset:528
	global_load_dwordx4 v[228:231], v166, s[86:87]
	global_load_dwordx4 v[232:235], v166, s[86:87] offset:16
	global_load_dwordx4 v[236:239], v166, s[86:87] offset:512
	global_load_dwordx4 v[240:243], v166, s[86:87] offset:528
	global_load_dwordx4 v[244:247], v167, s[86:87]
	global_load_dwordx4 v[248:251], v167, s[86:87] offset:16
	global_load_dwordx4 v[172:175], v167, s[86:87] offset:512
	global_load_dwordx4 v[176:179], v167, s[86:87] offset:528
	s_waitcnt vmcnt(16)
	v_pk_mul_f32 v[140:141], s[70:71], v[140:141]
	v_pk_mul_f32 v[142:143], s[78:79], v[142:143]
	v_pk_mul_f32 v[144:145], s[70:71], v[144:145]
	v_pk_mul_f32 v[146:147], s[78:79], v[146:147]
	v_pk_mul_f32 v[148:149], s[70:71], v[148:149]
	v_pk_mul_f32 v[150:151], s[78:79], v[150:151]
	v_pk_mul_f32 v[152:153], s[70:71], v[152:153]
	v_pk_mul_f32 v[154:155], s[78:79], v[154:155]
	s_waitcnt vmcnt(0)
	v_pk_fma_f32 v[126:127], v[126:127], v[140:141], v[196:197]
	v_pk_fma_f32 v[128:129], v[128:129], v[142:143], v[198:199]
	v_pk_fma_f32 v[122:123], v[122:123], v[144:145], v[200:201]
	v_pk_fma_f32 v[124:125], v[124:125], v[146:147], v[202:203]
	v_pk_fma_f32 v[110:111], v[110:111], v[148:149], v[204:205]
	v_pk_fma_f32 v[112:113], v[112:113], v[150:151], v[206:207]
	v_pk_fma_f32 v[106:107], v[106:107], v[152:153], v[208:209]
	v_pk_fma_f32 v[108:109], v[108:109], v[154:155], v[210:211]
	v_pk_fma_f32 v[118:119], v[118:119], v[140:141], v[212:213]
	v_pk_fma_f32 v[120:121], v[120:121], v[142:143], v[214:215]
	v_pk_fma_f32 v[114:115], v[114:115], v[144:145], v[216:217]
	v_pk_fma_f32 v[116:117], v[116:117], v[146:147], v[218:219]
	v_pk_fma_f32 v[102:103], v[102:103], v[148:149], v[220:221]
	v_pk_fma_f32 v[104:105], v[104:105], v[150:151], v[222:223]
	v_pk_fma_f32 v[98:99], v[98:99], v[152:153], v[224:225]
	v_pk_fma_f32 v[100:101], v[100:101], v[154:155], v[226:227]
	v_pk_fma_f32 v[94:95], v[94:95], v[140:141], v[228:229]
	v_pk_fma_f32 v[96:97], v[96:97], v[142:143], v[230:231]
	v_pk_fma_f32 v[90:91], v[90:91], v[144:145], v[232:233]
	v_pk_fma_f32 v[92:93], v[92:93], v[146:147], v[234:235]
	v_pk_fma_f32 v[78:79], v[78:79], v[148:149], v[236:237]
	v_pk_fma_f32 v[80:81], v[80:81], v[150:151], v[238:239]
	v_pk_fma_f32 v[74:75], v[74:75], v[152:153], v[240:241]
	v_pk_fma_f32 v[76:77], v[76:77], v[154:155], v[242:243]
	v_pk_fma_f32 v[86:87], v[86:87], v[140:141], v[244:245]
	v_pk_fma_f32 v[88:89], v[88:89], v[142:143], v[246:247]
	v_pk_fma_f32 v[82:83], v[82:83], v[144:145], v[248:249]
	v_pk_fma_f32 v[84:85], v[84:85], v[146:147], v[250:251]
	v_pk_fma_f32 v[70:71], v[70:71], v[148:149], v[172:173]
	v_pk_fma_f32 v[72:73], v[72:73], v[150:151], v[174:175]
	v_pk_fma_f32 v[66:67], v[66:67], v[152:153], v[176:177]
	v_pk_fma_f32 v[68:69], v[68:69], v[154:155], v[178:179]
	global_load_dwordx4 v[196:199], v156, s[86:87]
	global_load_dwordx4 v[200:203], v156, s[86:87] offset:16
	global_load_dwordx4 v[204:207], v156, s[86:87] offset:512
	global_load_dwordx4 v[208:211], v156, s[86:87] offset:528
	global_load_dwordx4 v[212:215], v157, s[86:87]
	global_load_dwordx4 v[216:219], v157, s[86:87] offset:16
	global_load_dwordx4 v[220:223], v157, s[86:87] offset:512
	global_load_dwordx4 v[224:227], v157, s[86:87] offset:528
	global_load_dwordx4 v[228:231], v158, s[86:87]
	global_load_dwordx4 v[232:235], v158, s[86:87] offset:16
	global_load_dwordx4 v[236:239], v158, s[86:87] offset:512
	global_load_dwordx4 v[240:243], v158, s[86:87] offset:528
	global_load_dwordx4 v[244:247], v159, s[86:87]
	global_load_dwordx4 v[248:251], v159, s[86:87] offset:16
	global_load_dwordx4 v[172:175], v159, s[86:87] offset:512
	global_load_dwordx4 v[176:179], v159, s[86:87] offset:528
	global_store_dwordx4 v160, v[126:129], s[84:85]
	global_store_dwordx4 v160, v[122:125], s[84:85] offset:16
	global_store_dwordx4 v160, v[110:113], s[84:85] offset:512
	global_store_dwordx4 v160, v[106:109], s[84:85] offset:528
	global_store_dwordx4 v161, v[118:121], s[84:85]
	global_store_dwordx4 v161, v[114:117], s[84:85] offset:16
	global_store_dwordx4 v161, v[102:105], s[84:85] offset:512
	global_store_dwordx4 v161, v[98:101], s[84:85] offset:528
	global_store_dwordx4 v166, v[94:97], s[84:85]
	global_store_dwordx4 v166, v[90:93], s[84:85] offset:16
	global_store_dwordx4 v166, v[78:81], s[84:85] offset:512
	global_store_dwordx4 v166, v[74:77], s[84:85] offset:528
	global_store_dwordx4 v167, v[86:89], s[84:85]
	global_store_dwordx4 v167, v[82:85], s[84:85] offset:16
	global_store_dwordx4 v167, v[70:73], s[84:85] offset:512
	global_store_dwordx4 v167, v[66:69], s[84:85] offset:528
	s_waitcnt vmcnt(16)
; #define PG8_BAR __builtin_amdgcn_s_barrier()
; template <class Epi>
; DI void gemm_phase(LAS unsigned char* lds, int tid, const Gemm g, const Order& S, const Epi& E) {
;     ...
;         E(acc, cur, wr, wc, fr, fq);
;         if (!has_next) break;
; #pragma unroll
;         for (int a = 0; a < 2; ++a)
; #pragma unroll
;             for (int b = 0; b < 2; ++b)
; #pragma unroll
;                 for (int m = 0; m < 4; ++m)
; #pragma unroll
;                     for (int n = 0; n < 2; ++n) acc[a][b][m][n] = (f32x4){0.f, 0.f, 0.f, 0.f};
;         cur = nxt; cA = nA; cB = nB; ++ui;
;         if (wr == 1) PG8_BAR;
;     DI void operator()(const f32x4 (&acc)[2][2][4][2], const Unit& u, int wr, int wc, int fr, int fq) const {
;     ...
;                 for (int m = 0; m < 2; ++m)
; #pragma unroll
;                     for (int bj = 0; bj < 2; ++bj)
; #pragma unroll
;                         for (int n = 0; n < 2; ++n) *(f32x4*)(dst + (size_t)(rloc + ai * HALF + (2 * mp + m) * 16) * DM + col0 + bj * HALF + 4 * n) = sv[m][bj][n] + gv[bj][n] * acc[ai][bj][2 * mp + m][n];
;             }
	v_pk_fma_f32 v[62:63], v[62:63], v[140:141], v[196:197]
	v_pk_fma_f32 v[64:65], v[64:65], v[142:143], v[198:199]
	v_pk_fma_f32 v[58:59], v[58:59], v[144:145], v[200:201]
	v_pk_fma_f32 v[60:61], v[60:61], v[146:147], v[202:203]
	v_pk_fma_f32 v[46:47], v[46:47], v[148:149], v[204:205]
	v_pk_fma_f32 v[48:49], v[48:49], v[150:151], v[206:207]
	v_pk_fma_f32 v[42:43], v[42:43], v[152:153], v[208:209]
	v_pk_fma_f32 v[44:45], v[44:45], v[154:155], v[210:211]
	v_pk_fma_f32 v[54:55], v[54:55], v[140:141], v[212:213]
	v_pk_fma_f32 v[56:57], v[56:57], v[142:143], v[214:215]
	v_pk_fma_f32 v[50:51], v[50:51], v[144:145], v[216:217]
	v_pk_fma_f32 v[52:53], v[52:53], v[146:147], v[218:219]
	v_pk_fma_f32 v[38:39], v[38:39], v[148:149], v[220:221]
	v_pk_fma_f32 v[40:41], v[40:41], v[150:151], v[222:223]
	v_pk_fma_f32 v[34:35], v[34:35], v[152:153], v[224:225]
	v_pk_fma_f32 v[36:37], v[36:37], v[154:155], v[226:227]
	v_pk_fma_f32 v[30:31], v[30:31], v[140:141], v[228:229]
	v_pk_fma_f32 v[32:33], v[32:33], v[142:143], v[230:231]
	v_pk_fma_f32 v[26:27], v[26:27], v[144:145], v[232:233]
	v_pk_fma_f32 v[28:29], v[28:29], v[146:147], v[234:235]
	v_pk_fma_f32 v[14:15], v[14:15], v[148:149], v[236:237]
	v_pk_fma_f32 v[16:17], v[16:17], v[150:151], v[238:239]
	v_pk_fma_f32 v[10:11], v[10:11], v[152:153], v[240:241]
	v_pk_fma_f32 v[12:13], v[12:13], v[154:155], v[242:243]
	v_pk_fma_f32 v[22:23], v[22:23], v[140:141], v[244:245]
	v_pk_fma_f32 v[24:25], v[24:25], v[142:143], v[246:247]
	v_pk_fma_f32 v[18:19], v[18:19], v[144:145], v[248:249]
	v_pk_fma_f32 v[20:21], v[20:21], v[146:147], v[250:251]
	v_pk_fma_f32 v[6:7], v[6:7], v[148:149], v[172:173]
	v_pk_fma_f32 v[8:9], v[8:9], v[150:151], v[174:175]
	v_pk_fma_f32 v[2:3], v[2:3], v[152:153], v[176:177]
	v_pk_fma_f32 v[4:5], v[4:5], v[154:155], v[178:179]
	global_store_dwordx4 v156, v[62:65], s[84:85]
	global_store_dwordx4 v156, v[58:61], s[84:85] offset:16
	global_store_dwordx4 v156, v[46:49], s[84:85] offset:512
	global_store_dwordx4 v156, v[42:45], s[84:85] offset:528
	global_store_dwordx4 v157, v[54:57], s[84:85]
	global_store_dwordx4 v157, v[50:53], s[84:85] offset:16
	global_store_dwordx4 v157, v[38:41], s[84:85] offset:512
	global_store_dwordx4 v157, v[34:37], s[84:85] offset:528
	global_store_dwordx4 v158, v[30:33], s[84:85]
	global_store_dwordx4 v158, v[26:29], s[84:85] offset:16
	global_store_dwordx4 v158, v[14:17], s[84:85] offset:512
	global_store_dwordx4 v158, v[10:13], s[84:85] offset:528
	global_store_dwordx4 v159, v[22:25], s[84:85]
	global_store_dwordx4 v159, v[18:21], s[84:85] offset:16
	global_store_dwordx4 v159, v[6:9], s[84:85] offset:512
	global_store_dwordx4 v159, v[2:5], s[84:85] offset:528
	s_and_b64 vcc, exec, s[4:5]
	s_cbranch_vccnz .Lres_nopf
	s_lshl_b32 s99, s19, 20
	s_lshl_b32 s33, s18, 10
	s_add_u32 s99, s99, s33
	v_lshrrev_b32_e32 v252, 3, v164
	v_and_b32_e32 v253, 7, v164
	v_lshlrev_b32_e32 v252, 12, v252
	v_lshl_add_u32 v252, v253, 7, v252
	v_add_u32_e32 v252, s99, v252
	global_load_dword v253, v252, s[86:87]
	v_add_u32_e32 v252, 0x40000, v252
	global_load_dword v253, v252, s[86:87]
	v_add_u32_e32 v252, 0x40000, v252
	global_load_dword v253, v252, s[86:87]
	v_add_u32_e32 v252, 0x40000, v252
	global_load_dword v253, v252, s[86:87]
.Lres_nopf:
	s_mov_b64 s[84:85], -1
	s_and_b64 vcc, exec, s[4:5]
	s_cbranch_vccnz .LBB0_485
	s_andn2_b64 vcc, exec, s[76:77]
	s_cbranch_vccnz .LBB0_484
	s_barrier
	s_branch .LBB0_484
